# stick-breaking half-tile loop: LDS-DMA source addresses from scalar base + two per-unit lane offsets (no per-half-tile 64-bit VALU address math)
# speedup vs baseline: 1.0066x; 1.0066x over previous
.LBB0_457:
	v_and_b32_e32 v96, 63, v34
	v_mov_b32_e32 v17, 0
	s_andn2_b64 vcc, exec, s[10:11]
	v_cmp_gt_u32_e64 s[10:11], 32, v96
	v_mov_b32_e32 v16, 0
	v_mov_b32_e32 v15, 0
	v_mov_b32_e32 v14, 0
	v_mov_b32_e32 v13, 0
	v_mov_b32_e32 v12, 0
	v_mov_b32_e32 v11, 0
	v_mov_b32_e32 v10, 0
	v_mov_b32_e32 v9, 0
	v_mov_b32_e32 v8, 0
	v_mov_b32_e32 v7, 0
	v_mov_b32_e32 v6, 0
	v_mov_b32_e32 v5, 0
	v_mov_b32_e32 v4, 0
	v_mov_b32_e32 v3, 0
	v_mov_b32_e32 v2, 0
	v_mov_b32_e32 v33, 0
	v_mov_b32_e32 v32, 0
	v_mov_b32_e32 v31, 0
	v_mov_b32_e32 v30, 0
	v_mov_b32_e32 v29, 0
	v_mov_b32_e32 v28, 0
	v_mov_b32_e32 v27, 0
	v_mov_b32_e32 v26, 0
	v_mov_b32_e32 v25, 0
	v_mov_b32_e32 v24, 0
	v_mov_b32_e32 v23, 0
	v_mov_b32_e32 v22, 0
	v_mov_b32_e32 v21, 0
	v_mov_b32_e32 v20, 0
	v_mov_b32_e32 v19, 0
	v_mov_b32_e32 v18, 0
	s_cbranch_vccnz .LBB0_471
	v_lshlrev_b32_e32 v4, 1, v34
	v_and_b32_e32 v0, 7, v34
	v_and_b32_e32 v99, 32, v4
	v_lshlrev_b32_e32 v4, 3, v34
	v_and_b32_e32 v100, 24, v4
	v_xor_b32_e32 v4, v35, v0
	v_lshlrev_b32_e32 v101, 4, v4
	v_bitop3_b32 v4, v35, v0, 2 bitop3:0x36
	v_lshlrev_b32_e32 v102, 4, v4
	v_bitop3_b32 v4, v35, v0, 4 bitop3:0x36
	v_bitop3_b32 v0, v35, v0, 6 bitop3:0x36
	v_lshlrev_b32_e32 v104, 4, v0
	v_lshlrev_b32_e32 v0, 5, v34
	v_and_b32_e32 v0, 0x180, v0
	v_lshlrev_b32_e32 v2, 3, v37
	v_lshlrev_b32_e32 v3, 3, v36
	v_lshl_or_b32 v105, v35, 9, v0
	v_lshlrev_b32_e32 v0, 4, v34
	v_mov_b32_e32 v18, 0
	v_lshlrev_b32_e32 v98, 7, v92
	v_lshlrev_b32_e32 v103, 4, v4
	v_and_b32_e32 v106, 64, v0
	v_bitop3_b32 v107, v0, 64, v0 bitop3:0xc
	s_mov_b32 s78, 0
	s_sub_i32 s86, 0, s12
	v_mov_b32_e32 v108, 1.0
	v_lshlrev_b32_e32 v0, 1, v2
	v_lshlrev_b32_e32 v84, 1, v3
	v_mad_u32_u24 v150, v83, s83, v0
	v_mad_u32_u24 v151, v83, s83, v84
	s_mov_b32 s87, s85
	v_mov_b32_e32 v19, v18
	v_mov_b32_e32 v20, v18
	v_mov_b32_e32 v21, v18
	v_mov_b32_e32 v22, v18
	v_mov_b32_e32 v23, v18
	v_mov_b32_e32 v24, v18
	v_mov_b32_e32 v25, v18
	v_mov_b32_e32 v26, v18
	v_mov_b32_e32 v27, v18
	v_mov_b32_e32 v28, v18
	v_mov_b32_e32 v29, v18
	v_mov_b32_e32 v30, v18
	v_mov_b32_e32 v31, v18
	v_mov_b32_e32 v32, v18
	v_mov_b32_e32 v33, v18
	v_mov_b32_e32 v2, v18
	v_mov_b32_e32 v3, v18
	v_mov_b32_e32 v4, v18
	v_mov_b32_e32 v5, v18
	v_mov_b32_e32 v6, v18
	v_mov_b32_e32 v7, v18
	v_mov_b32_e32 v8, v18
	v_mov_b32_e32 v9, v18
	v_mov_b32_e32 v10, v18
	v_mov_b32_e32 v11, v18
	v_mov_b32_e32 v12, v18
	v_mov_b32_e32 v13, v18
	v_mov_b32_e32 v14, v18
	v_mov_b32_e32 v15, v18
	v_mov_b32_e32 v16, v18
	v_mov_b32_e32 v17, v18
	s_cmp_eq_u32 s86, 0
	s_cbranch_scc1 .LBB0_469
.LBB0_459:
	s_add_i32 s12, s87, s72
	s_sub_i32 s14, s12, 32
	s_lshl_b32 s15, s78, 13
	s_xor_b32 s12, s15, 0x2000
	s_add_i32 s16, s12, s73
	s_mov_b32 s75, s77
	v_mov_b32_e32 v85, v1
	s_mul_i32 s98, s14, s83
	s_mul_hi_u32 s99, s14, s83
	s_add_u32 s98, s98, s68
	s_addc_u32 s99, s99, s69
	s_add_u32 s98, s98, s76
	s_addc_u32 s99, s99, 0
	s_add_u32 s100, s98, 0x400
	s_addc_u32 s101, s99, 0
	s_mov_b32 s13, m0
	s_mov_b32 m0, s16
	s_add_i32 s12, s16, 0x400
	global_load_lds_dwordx4 v150, s[98:99]
	s_mov_b32 m0, s12
	s_add_u32 s98, s98, 0xe000
	s_addc_u32 s99, s99, 0
	global_load_lds_dwordx4 v150, s[98:99]
	s_add_i32 m0, s16, 0x800
	s_add_u32 s98, s98, 0xe000
	s_addc_u32 s99, s99, 0
	global_load_lds_dwordx4 v150, s[98:99]
	s_add_i32 m0, s16, 0xc00
	s_add_u32 s98, s98, 0xe000
	s_addc_u32 s99, s99, 0
	global_load_lds_dwordx4 v150, s[98:99]
	s_add_i32 m0, s16, 0x1000
	s_nop 0
	global_load_lds_dwordx4 v151, s[100:101]
	s_add_i32 m0, s16, 0x1400
	s_add_u32 s100, s100, 0xe000
	s_addc_u32 s101, s101, 0
	global_load_lds_dwordx4 v151, s[100:101]
	s_add_i32 m0, s16, 0x1800
	s_add_u32 s100, s100, 0xe000
	s_addc_u32 s101, s101, 0
	global_load_lds_dwordx4 v151, s[100:101]
	s_add_i32 m0, s16, 0x1c00
	s_add_u32 s100, s100, 0xe000
	s_addc_u32 s101, s101, 0
	global_load_lds_dwordx4 v151, s[100:101]
	s_mov_b32 m0, s13
	s_waitcnt vmcnt(8)
	s_mov_b32 s14, s87
	s_cbranch_execnz .LBB0_461

	.amdhsa_kernel _Z9hymba_fwd4Args
		.amdhsa_group_segment_fixed_size 0
		.amdhsa_private_segment_fixed_size 0
		.amdhsa_kernarg_size 408
		.amdhsa_user_sgpr_count 2
		.amdhsa_user_sgpr_dispatch_ptr 0
		.amdhsa_user_sgpr_queue_ptr 0
		.amdhsa_user_sgpr_kernarg_segment_ptr 1
		.amdhsa_user_sgpr_dispatch_id 0
		.amdhsa_user_sgpr_kernarg_preload_length 0
		.amdhsa_user_sgpr_kernarg_preload_offset 0
		.amdhsa_user_sgpr_private_segment_size 0
		.amdhsa_uses_dynamic_stack 0
		.amdhsa_enable_private_segment 0
		.amdhsa_system_sgpr_workgroup_id_x 1
		.amdhsa_system_sgpr_workgroup_id_y 0
		.amdhsa_system_sgpr_workgroup_id_z 0
		.amdhsa_system_sgpr_workgroup_info 0
		.amdhsa_system_vgpr_workitem_id 2
		.amdhsa_next_free_vgpr 256
		.amdhsa_next_free_sgpr 102
		.amdhsa_accum_offset 256
		.amdhsa_reserve_vcc 1
		.amdhsa_float_round_mode_32 0
		.amdhsa_float_round_mode_16_64 0
		.amdhsa_float_denorm_mode_32 3
		.amdhsa_float_denorm_mode_16_64 3
		.amdhsa_dx10_clamp 1
		.amdhsa_ieee_mode 1
		.amdhsa_fp16_overflow 0
		.amdhsa_tg_split 0
		.amdhsa_exception_fp_ieee_invalid_op 0
		.amdhsa_exception_fp_denorm_src 0
		.amdhsa_exception_fp_ieee_div_zero 0
		.amdhsa_exception_fp_ieee_overflow 0
		.amdhsa_exception_fp_ieee_underflow 0
		.amdhsa_exception_fp_ieee_inexact 0
		.amdhsa_exception_int_div_zero 0
	.end_amdhsa_kernel

amdhsa.kernels:
  - .agpr_count:     0
    .args:
      - .offset:         0
        .size:           152
        .value_kind:     by_value
      - .offset:         152
        .size:           4
        .value_kind:     hidden_block_count_x
      - .offset:         156
        .size:           4
        .value_kind:     hidden_block_count_y
      - .offset:         160
        .size:           4
        .value_kind:     hidden_block_count_z
      - .offset:         164
        .size:           2
        .value_kind:     hidden_group_size_x
      - .offset:         166
        .size:           2
        .value_kind:     hidden_group_size_y
      - .offset:         168
        .size:           2
        .value_kind:     hidden_group_size_z
      - .offset:         170
        .size:           2
        .value_kind:     hidden_remainder_x
      - .offset:         172
        .size:           2
        .value_kind:     hidden_remainder_y
      - .offset:         174
        .size:           2
        .value_kind:     hidden_remainder_z
      - .offset:         192
        .size:           8
        .value_kind:     hidden_global_offset_x
      - .offset:         200
        .size:           8
        .value_kind:     hidden_global_offset_y
      - .offset:         208
        .size:           8
        .value_kind:     hidden_global_offset_z
      - .offset:         216
        .size:           2
        .value_kind:     hidden_grid_dims
      - .offset:         240
        .size:           8
        .value_kind:     hidden_multigrid_sync_arg
      - .offset:         272
        .size:           4
        .value_kind:     hidden_dynamic_lds_size
    .group_segment_fixed_size: 0
    .kernarg_segment_align: 8
    .kernarg_segment_size: 408
    .language:       OpenCL C
    .language_version:
      - 2
      - 0
    .max_flat_workgroup_size: 512
    .name:           _Z9hymba_fwd4Args
    .private_segment_fixed_size: 0
    .sgpr_count:     108
    .sgpr_spill_count: 52
    .symbol:         _Z9hymba_fwd4Args.kd
    .uniform_work_group_size: 1
    .uses_dynamic_stack: false
    .vgpr_count:     256
    .vgpr_spill_count: 0
    .wavefront_size: 64
